# P1/P6 tile order: groups of 4 row panels (WGM 4 instead of 2) to share more weight panels per XCD round
# speedup vs baseline: 1.0015x; 1.0015x over previous
.LBB0_110:
	s_or_b64 exec, exec, s[0:1]
	s_add_u32 s26, s30, 0x7000000
	s_addc_u32 s27, s31, 0
	v_mov_b32_e32 v9, v242
	s_cmpk_lt_i32 s2, 0xb00
	s_waitcnt lgkmcnt(0)
	s_barrier
	s_cselect_b64 s[46:47], -1, 0
	s_cmpk_gt_i32 s2, 0xaff
	v_readfirstlane_b32 s1, v9
	s_cbranch_scc1 .LBB0_126
	v_lshlrev_b32_e32 v0, 4, v9
	v_add_u32_e32 v1, 0x2000, v0
	v_ashrrev_i32_e32 v2, 31, v1
	v_lshrrev_b32_e32 v2, 22, v2
	v_add_u32_e32 v2, v1, v2
	v_ashrrev_i32_e32 v8, 10, v2
	v_mul_i32_i24_e32 v2, 0x400, v8
	v_sub_u32_e32 v1, v1, v2
	v_lshrrev_b32_e32 v2, 4, v1
	v_bitop3_b32 v1, v2, v1, 32 bitop3:0x6c
	v_ashrrev_i32_e32 v2, 31, v1
	v_lshrrev_b32_e32 v2, 26, v2
	v_add_u32_e32 v2, v1, v2
	v_lshlrev_b32_e32 v3, 3, v8
	v_ashrrev_i32_e32 v10, 6, v2
	v_and_b32_e32 v3, -16, v3
	v_add_u32_e32 v3, v10, v3
	v_and_b32_e32 v4, 3, v10
	s_mov_b32 s0, 0x1fffe0
	v_lshrrev_b32_e32 v5, 2, v3
	v_lshlrev_b32_e32 v6, 1, v3
	v_and_b32_e32 v2, 0xc0, v2
	v_and_or_b32 v4, v3, s0, v4
	v_and_b32_e32 v5, 4, v5
	v_and_b32_e32 v6, 24, v6
	v_sub_u32_e32 v1, v1, v2
	v_mov_b32_e32 v2, 1
	v_or3_b32 v4, v4, v5, v6
	v_lshlrev_b32_e32 v5, 5, v8
	v_ashrrev_i16_sdwa v1, v2, sext(v1) dst_sel:DWORD dst_unused:UNUSED_PAD src0_sel:DWORD src1_sel:BYTE_0
	v_and_b32_e32 v5, 32, v5
	v_bfe_i32 v11, v1, 0, 16
	v_add_lshl_u32 v1, v5, v11, 1
	v_lshl_add_u32 v128, v4, 11, v1
	v_lshl_add_u32 v130, v3, 11, v1
	v_bfe_i32 v1, v9, 27, 1
	v_lshrrev_b32_e32 v1, 22, v1
	v_add_u32_e32 v1, v0, v1
	v_and_b32_e32 v1, 0xfffffc00, v1
	v_sub_u32_e32 v0, v0, v1
	v_lshrrev_b32_e32 v1, 4, v0
	v_ashrrev_i32_e32 v3, 31, v9
	v_bitop3_b32 v0, v1, v0, 32 bitop3:0x6c
	v_lshrrev_b32_e32 v3, 26, v3
	v_ashrrev_i32_e32 v1, 31, v0
	v_add_u32_e32 v3, v9, v3
	v_lshrrev_b32_e32 v1, 26, v1
	v_ashrrev_i32_e32 v13, 6, v3
	v_add_u32_e32 v1, v0, v1
	v_lshlrev_b32_e32 v3, 3, v13
	v_ashrrev_i32_e32 v12, 6, v1
	v_and_b32_e32 v3, -16, v3
	v_add_u32_e32 v3, v12, v3
	v_and_b32_e32 v4, 3, v12
	s_ashr_i32 s61, s2, 31
	v_and_or_b32 v4, v3, s0, v4
	s_lshr_b32 s0, s61, 29
	s_add_i32 s0, s2, s0
	s_ashr_i32 s6, s1, 6
	s_ashr_i32 s4, s0, 3
	s_and_b32 s0, s0, -8
	s_ashr_i32 s8, s1, 8
	s_lshl_b32 s60, s6, 10
	s_sub_i32 s0, s2, s0
	s_cmp_lt_i32 s0, 0
	s_movk_i32 s62, 0x161
	s_cselect_b32 s5, s62, 0x160
	s_mul_i32 s0, s0, s5
	s_add_i32 s0, s0, s4
	s_mul_i32 s4, s0, 0xba3
	s_lshr_b32 s4, s4, 18
	s_mul_i32 s5, s4, 0x58
	s_sub_i32 s0, s0, s5
	s_and_b32 s5, s0, 3
	s_lshl_b32 s4, s4, 2
	s_add_i32 s50, s5, s4
	s_lshr_b32 s0, s0, 2
	v_lshrrev_b32_e32 v5, 2, v3
	v_lshlrev_b32_e32 v6, 1, v3
	v_and_b32_e32 v1, 0xc0, v1
	v_and_b32_e32 v5, 4, v5
	v_and_b32_e32 v6, 24, v6
	v_sub_u32_e32 v0, v0, v1
	s_ashr_i32 s51, s50, 31
	s_bfe_i64 s[16:17], s[0:1], 0x100000
	v_or3_b32 v4, v4, v5, v6
	v_lshlrev_b32_e32 v5, 5, v13
	v_ashrrev_i16_sdwa v0, v2, sext(v0) dst_sel:DWORD dst_unused:UNUSED_PAD src0_sel:DWORD src1_sel:BYTE_0
	s_lshl_b64 s[4:5], s[50:51], 19
	s_lshl_b64 s[16:17], s[16:17], 19
	v_and_b32_e32 v5, 32, v5
	v_bfe_i32 v14, v0, 0, 16
	s_add_u32 s56, s14, s16
	v_add_lshl_u32 v0, v5, v14, 1
	s_addc_u32 s57, s15, s17
	s_add_i32 s51, s60, 0
	v_lshl_add_u32 v132, v4, 11, v0
	s_add_i32 m0, s51, 0x10000
	v_lshl_add_u32 v134, v3, 11, v0
	global_load_lds_dwordx4 v132, s[56:57]
	s_add_i32 m0, s51, 0x12000
	s_add_u32 s16, s56, 0x40000
	global_load_lds_dwordx4 v128, s[56:57]
	s_addc_u32 s17, s57, 0
	s_add_i32 m0, s51, 0x14000
	v_mov_b32_e32 v133, 0
	global_load_lds_dwordx4 v132, s[16:17]
	s_add_i32 m0, s51, 0x16000
	s_add_u32 s54, s24, s4
	s_addc_u32 s55, s25, s5
	s_add_i32 s63, s51, 0x2000
	global_load_lds_dwordx4 v128, s[16:17]
	s_mov_b32 m0, s51
	s_add_u32 s4, s54, 0x40000
	global_load_lds_dwordx4 v134, s[54:55]
	s_mov_b32 m0, s63
	s_addc_u32 s5, s55, 0
	s_add_i32 s64, s51, 0x4000
	global_load_lds_dwordx4 v130, s[54:55]
	s_mov_b32 m0, s64
	s_add_i32 s65, s51, 0x6000
	global_load_lds_dwordx4 v134, s[4:5]
	s_mov_b32 m0, s65
	v_mov_b32_e32 v129, v133
	global_load_lds_dwordx4 v130, s[4:5]
	v_mov_b32_e32 v135, v133
	v_mov_b32_e32 v131, v133
	s_cmp_eq_u32 s8, 1
	s_mov_b32 s76, 0
	v_lshl_add_u64 v[6:7], s[56:57], 0, v[132:133]
	v_lshl_add_u64 v[4:5], s[56:57], 0, v[128:129]
	v_lshl_add_u64 v[0:1], s[54:55], 0, v[134:135]
	s_cselect_b64 s[4:5], -1, 0
	s_cmp_lg_u32 s8, 1
	v_lshl_add_u64 v[2:3], s[54:55], 0, v[130:131]
	s_cbranch_scc1 .LBB0_113
	s_barrier

.LBB0_116:
	s_add_i32 s76, s76, 1
	s_mul_i32 s0, s76, s79
	s_mul_hi_u32 s1, s76, s80
	s_add_i32 s1, s1, s0
	s_mul_i32 s0, s76, s80
	s_add_u32 s22, s0, s2
	s_addc_u32 s23, s1, s61
	v_cmp_gt_i64_e32 vcc, s[22:23], v[142:143]
	v_cmp_lt_i64_e64 s[0:1], s[22:23], v[140:141]
	s_cbranch_vccnz .LBB0_118
	s_and_b32 s16, s22, 7
	s_lshr_b32 s17, s22, 3
	s_mul_i32 s16, s16, 0x160
	s_add_i32 s16, s16, s17
	s_mul_i32 s17, s16, 0xba3
	s_lshr_b32 s17, s17, 18
	s_mul_i32 s18, s17, 0x58
	s_sub_i32 s16, s16, s18
	s_and_b32 s18, s16, 3
	s_lshl_b32 s17, s17, 2
	s_add_i32 s18, s18, s17
	s_lshr_b32 s16, s16, 2

.LBB0_712:
	s_or_b64 exec, exec, s[4:5]
	v_mov_b32_e32 v10, v242
	s_waitcnt lgkmcnt(0)
	s_barrier
	s_andn2_b64 vcc, exec, s[46:47]
	v_readfirstlane_b32 s5, v10
	s_cbranch_vccnz .LBB0_728
	v_lshlrev_b32_e32 v0, 4, v10
	v_add_u32_e32 v1, 0x2000, v0
	v_ashrrev_i32_e32 v2, 31, v1
	v_lshrrev_b32_e32 v2, 22, v2
	v_add_u32_e32 v2, v1, v2
	v_ashrrev_i32_e32 v8, 10, v2
	v_mul_i32_i24_e32 v2, 0x400, v8
	v_sub_u32_e32 v1, v1, v2
	v_lshrrev_b32_e32 v2, 4, v1
	v_bitop3_b32 v1, v2, v1, 32 bitop3:0x6c
	v_ashrrev_i32_e32 v2, 31, v1
	v_lshrrev_b32_e32 v2, 26, v2
	v_add_u32_e32 v2, v1, v2
	v_lshlrev_b32_e32 v3, 3, v8
	v_ashrrev_i32_e32 v9, 6, v2
	v_and_b32_e32 v3, -16, v3
	v_add_u32_e32 v3, v9, v3
	v_and_b32_e32 v4, 3, v9
	s_mov_b32 s4, 0x1fffe0
	v_lshrrev_b32_e32 v5, 2, v3
	v_lshlrev_b32_e32 v6, 1, v3
	v_and_b32_e32 v2, 0xc0, v2
	v_and_or_b32 v4, v3, s4, v4
	v_and_b32_e32 v5, 4, v5
	v_and_b32_e32 v6, 24, v6
	v_sub_u32_e32 v1, v1, v2
	v_mov_b32_e32 v2, 1
	v_or3_b32 v4, v4, v5, v6
	v_lshlrev_b32_e32 v5, 5, v8
	v_ashrrev_i16_sdwa v1, v2, sext(v1) dst_sel:DWORD dst_unused:UNUSED_PAD src0_sel:DWORD src1_sel:BYTE_0
	v_and_b32_e32 v5, 32, v5
	v_bfe_i32 v11, v1, 0, 16
	v_add_lshl_u32 v1, v5, v11, 1
	v_lshl_add_u32 v128, v4, 11, v1
	v_lshl_add_u32 v130, v3, 11, v1
	v_bfe_i32 v1, v10, 27, 1
	v_lshrrev_b32_e32 v1, 22, v1
	v_add_u32_e32 v1, v0, v1
	v_and_b32_e32 v1, 0xfffffc00, v1
	v_sub_u32_e32 v0, v0, v1
	v_lshrrev_b32_e32 v1, 4, v0
	v_ashrrev_i32_e32 v3, 31, v10
	v_bitop3_b32 v0, v1, v0, 32 bitop3:0x6c
	v_lshrrev_b32_e32 v3, 26, v3
	v_ashrrev_i32_e32 v1, 31, v0
	v_add_u32_e32 v3, v10, v3
	v_lshrrev_b32_e32 v1, 26, v1
	s_waitcnt vmcnt(0)
	v_ashrrev_i32_e32 v13, 6, v3
	v_add_u32_e32 v1, v0, v1
	v_lshlrev_b32_e32 v3, 3, v13
	v_ashrrev_i32_e32 v12, 6, v1
	v_and_b32_e32 v3, -16, v3
	v_add_u32_e32 v3, v12, v3
	v_and_b32_e32 v4, 3, v12
	s_ashr_i32 s43, s2, 31
	v_and_or_b32 v4, v3, s4, v4
	s_lshr_b32 s4, s43, 29
	s_add_i32 s4, s2, s4
	s_ashr_i32 s8, s5, 6
	s_ashr_i32 s6, s4, 3
	s_and_b32 s4, s4, -8
	s_ashr_i32 s10, s5, 8
	s_lshl_b32 s42, s8, 10
	s_sub_i32 s4, s2, s4
	s_cmp_lt_i32 s4, 0
	s_movk_i32 s44, 0x161
	s_cselect_b32 s7, s44, 0x160
	s_mul_i32 s4, s4, s7
	s_add_i32 s4, s4, s6
	s_mul_i32 s6, s4, 0xba3
	s_lshr_b32 s6, s6, 18
	s_mul_i32 s7, s6, 0x58
	s_sub_i32 s4, s4, s7
	s_and_b32 s7, s4, 3
	s_lshl_b32 s6, s6, 2
	s_add_i32 s18, s7, s6
	s_lshr_b32 s4, s4, 2
	v_lshrrev_b32_e32 v5, 2, v3
	v_lshlrev_b32_e32 v6, 1, v3
	v_and_b32_e32 v1, 0xc0, v1
	v_and_b32_e32 v5, 4, v5
	v_and_b32_e32 v6, 24, v6
	v_sub_u32_e32 v0, v0, v1
	s_ashr_i32 s19, s18, 31
	s_bfe_i64 s[12:13], s[4:5], 0x100000
	v_or3_b32 v4, v4, v5, v6
	v_lshlrev_b32_e32 v5, 5, v13
	v_ashrrev_i16_sdwa v0, v2, sext(v0) dst_sel:DWORD dst_unused:UNUSED_PAD src0_sel:DWORD src1_sel:BYTE_0
	s_lshl_b64 s[6:7], s[18:19], 19
	s_lshl_b64 s[12:13], s[12:13], 19
	v_and_b32_e32 v5, 32, v5
	v_bfe_i32 v14, v0, 0, 16
	s_add_u32 s38, s70, s12
	v_add_lshl_u32 v0, v5, v14, 1
	s_addc_u32 s39, s71, s13
	s_add_i32 s19, s42, 0
	v_lshl_add_u32 v132, v4, 11, v0
	s_add_i32 m0, s19, 0x10000
	v_lshl_add_u32 v134, v3, 11, v0
	global_load_lds_dwordx4 v132, s[38:39]
	s_add_i32 m0, s19, 0x12000
	s_add_u32 s12, s38, 0x40000
	global_load_lds_dwordx4 v128, s[38:39]
	s_addc_u32 s13, s39, 0
	s_add_i32 m0, s19, 0x14000
	v_mov_b32_e32 v133, 0
	global_load_lds_dwordx4 v132, s[12:13]
	s_add_i32 m0, s19, 0x16000
	s_add_u32 s36, s24, s6
	s_addc_u32 s37, s25, s7
	s_add_i32 s45, s19, 0x2000
	global_load_lds_dwordx4 v128, s[12:13]
	s_mov_b32 m0, s19
	s_add_u32 s6, s36, 0x40000
	global_load_lds_dwordx4 v134, s[36:37]
	s_mov_b32 m0, s45
	s_addc_u32 s7, s37, 0
	s_add_i32 s46, s19, 0x4000
	global_load_lds_dwordx4 v130, s[36:37]
	s_mov_b32 m0, s46
	s_add_i32 s47, s19, 0x6000
	global_load_lds_dwordx4 v134, s[6:7]
	s_mov_b32 m0, s47
	v_mov_b32_e32 v129, v133
	global_load_lds_dwordx4 v130, s[6:7]
	v_mov_b32_e32 v135, v133
	v_mov_b32_e32 v131, v133
	s_cmp_eq_u32 s10, 1
	s_mov_b32 s48, 0
	v_lshl_add_u64 v[6:7], s[38:39], 0, v[132:133]
	v_lshl_add_u64 v[4:5], s[38:39], 0, v[128:129]
	v_lshl_add_u64 v[0:1], s[36:37], 0, v[134:135]
	s_cselect_b64 s[6:7], -1, 0
	s_cmp_lg_u32 s10, 1
	v_lshl_add_u64 v[2:3], s[36:37], 0, v[130:131]
	s_cbranch_scc1 .LBB0_715
	s_barrier

.LBB0_718:
	s_add_i32 s48, s48, 1
	s_mul_i32 s1, s48, s51
	s_mul_hi_u32 s4, s48, s52
	s_add_i32 s4, s4, s1
	s_mul_i32 s1, s48, s52
	s_add_u32 s14, s1, s2
	s_addc_u32 s15, s4, s43
	v_cmp_gt_i64_e32 vcc, s[14:15], v[144:145]
	v_cmp_lt_i64_e64 s[4:5], s[14:15], v[142:143]
	s_cbranch_vccnz .LBB0_720
	s_and_b32 s0, s14, 7
	s_lshr_b32 s1, s14, 3
	s_mul_i32 s0, s0, 0x160
	s_add_i32 s0, s0, s1
	s_mul_i32 s1, s0, 0xba3
	s_lshr_b32 s1, s1, 18
	s_mul_i32 s12, s1, 0x58
	s_sub_i32 s0, s0, s12
	s_and_b32 s12, s0, 3
	s_lshl_b32 s1, s1, 2
	s_add_i32 s12, s12, s1
	s_lshr_b32 s0, s0, 2
